# rowsel: non-diagonal partially-selected tiles skip per-key masking in nsa+moba (unselected rows forced to p=0 via -inf max/offset)
# speedup vs baseline: 1.0034x; 1.0034x over previous
.LBB0_830:
	s_or_b32 s12, s44, 63
	s_sub_i32 s45, s26, s12
	s_cmp_lt_i32 s45, s27
	s_cselect_b64 s[52:53], -1, 0
	s_and_b64 s[4:5], s[52:53], s[4:5]
	s_andn2_b64 vcc, exec, s[4:5]
	s_cbranch_vccnz .LBB0_844
	v_add_u32_e32 v236, v209, v0
	ds_read_b128 v[132:135], v236
	ds_read_b128 v[186:189], v236 offset:64
	ds_read_b128 v[140:143], v236 offset:4608
	ds_read_b128 v[148:151], v236 offset:9216
	ds_read_b128 v[156:159], v236 offset:13824
	s_cmp_lt_i32 s26, s12
	s_cselect_b64 s[52:53], -1, 0
	s_sub_i32 s4, s57, s44
	s_cmp_ge_i32 s4, s27
	s_waitcnt lgkmcnt(4)
	v_mfma_f32_16x16x32_bf16 v[136:139], v[132:135], v[8:11], 0
	s_cselect_b64 s[4:5], -1, 0
	s_mov_b64 s[38:39], s[52:53]
	s_or_b64 s[4:5], s[38:39], s[4:5]
	v_mfma_f32_16x16x32_bf16 v[132:135], v[132:135], v[24:27], 0
	s_mov_b64 s[38:39], -1
	s_and_b64 vcc, exec, s[4:5]
	s_waitcnt lgkmcnt(3)
	v_mfma_f32_16x16x32_bf16 v[136:139], v[186:189], v[12:15], v[136:139]
	v_mfma_f32_16x16x32_bf16 v[132:135], v[186:189], v[28:31], v[132:135]
	ds_read_b128 v[186:189], v236 offset:4672
	s_waitcnt lgkmcnt(3)
	v_mfma_f32_16x16x32_bf16 v[144:147], v[140:143], v[8:11], 0
	v_mfma_f32_16x16x32_bf16 v[140:143], v[140:143], v[24:27], 0
	s_waitcnt lgkmcnt(0)
	v_mfma_f32_16x16x32_bf16 v[144:147], v[186:189], v[12:15], v[144:147]
	v_mfma_f32_16x16x32_bf16 v[140:143], v[186:189], v[28:31], v[140:143]
	ds_read_b128 v[186:189], v236 offset:9280
	v_mfma_f32_16x16x32_bf16 v[152:155], v[148:151], v[8:11], 0
	v_mfma_f32_16x16x32_bf16 v[148:151], v[148:151], v[24:27], 0
	s_waitcnt lgkmcnt(0)
	v_mfma_f32_16x16x32_bf16 v[152:155], v[186:189], v[12:15], v[152:155]
	v_mfma_f32_16x16x32_bf16 v[148:151], v[186:189], v[28:31], v[148:151]
	ds_read_b128 v[186:189], v236 offset:13888
	v_mfma_f32_16x16x32_bf16 v[160:163], v[156:159], v[8:11], 0
	v_mfma_f32_16x16x32_bf16 v[156:159], v[156:159], v[24:27], 0
	s_waitcnt lgkmcnt(0)
	v_mfma_f32_16x16x32_bf16 v[160:163], v[186:189], v[12:15], v[160:163]
	v_mfma_f32_16x16x32_bf16 v[156:159], v[186:189], v[28:31], v[156:159]
	ds_read_b128 v[186:189], v236 offset:128
	s_waitcnt lgkmcnt(0)
	v_mfma_f32_16x16x32_bf16 v[136:139], v[186:189], v[16:19], v[136:139]
	v_mfma_f32_16x16x32_bf16 v[132:135], v[186:189], v[32:35], v[132:135]
	ds_read_b128 v[186:189], v236 offset:4736
	s_waitcnt lgkmcnt(0)
	v_mfma_f32_16x16x32_bf16 v[144:147], v[186:189], v[16:19], v[144:147]
	v_mfma_f32_16x16x32_bf16 v[140:143], v[186:189], v[32:35], v[140:143]
	ds_read_b128 v[186:189], v236 offset:9344
	s_waitcnt lgkmcnt(0)
	v_mfma_f32_16x16x32_bf16 v[218:221], v[186:189], v[16:19], v[152:155]
	s_nop 2
	ds_read_b128 v[152:155], v236 offset:192
	v_mfma_f32_16x16x32_bf16 v[186:189], v[186:189], v[32:35], v[148:151]
	s_nop 2
	ds_read_b128 v[148:151], v236 offset:13952
	s_waitcnt lgkmcnt(0)
	v_mfma_f32_16x16x32_bf16 v[160:163], v[148:151], v[16:19], v[160:163]
	v_mfma_f32_16x16x32_bf16 v[222:225], v[148:151], v[32:35], v[156:159]
	v_mfma_f32_16x16x32_bf16 v[148:151], v[152:155], v[20:23], v[136:139]
	s_nop 2
	ds_read_b128 v[136:139], v236 offset:4800
	v_mfma_f32_16x16x32_bf16 v[132:135], v[152:155], v[36:39], v[132:135]
	s_waitcnt lgkmcnt(0)
	v_mfma_f32_16x16x32_bf16 v[152:155], v[136:139], v[20:23], v[144:147]
	s_nop 2
	ds_read_b128 v[144:147], v236 offset:14016
	v_mfma_f32_16x16x32_bf16 v[136:139], v[136:139], v[36:39], v[140:143]
	s_nop 2
	ds_read_b128 v[140:143], v236 offset:9408
	s_waitcnt lgkmcnt(0)
	v_mfma_f32_16x16x32_bf16 v[156:159], v[140:143], v[20:23], v[218:221]
	v_mfma_f32_16x16x32_bf16 v[140:143], v[140:143], v[36:39], v[186:189]
	v_mfma_f32_16x16x32_bf16 v[160:163], v[144:147], v[20:23], v[160:163]
	v_mfma_f32_16x16x32_bf16 v[144:147], v[144:147], v[36:39], v[222:225]
	s_cbranch_vccnz .LBB0_833
	v_max_f32_e32 v186, v151, v151
	v_max_f32_e32 v187, v150, v150
	v_max_f32_e32 v186, v187, v186
	v_max_f32_e32 v187, v155, v155
	v_max_f32_e32 v188, v154, v154
	v_max_f32_e32 v187, v188, v187
	v_max3_f32 v186, v148, v149, v186
	v_max3_f32 v187, v152, v153, v187
	v_max3_f32 v186, v186, s88, v187
	v_max_f32_e32 v187, v159, v159
	v_max_f32_e32 v188, v158, v158
	v_max_f32_e32 v187, v188, v187
	v_max_f32_e32 v188, v163, v163
	v_max_f32_e32 v189, v162, v162
	v_max_f32_e32 v188, v189, v188
	v_max3_f32 v187, v156, v157, v187
	v_max3_f32 v188, v160, v161, v188
	v_max3_f32 v236, v186, v187, v188
	v_mov_b32_e32 v237, 0x7f800000
	s_andn2_b64 vcc, exec, s[40:41]
	s_cbranch_vccnz .Lrs_nsa_0_0
	v_lshrrev_b32_e32 v238, s68, v179
	v_lshlrev_b32_e32 v238, 31, v238
	v_xor_b32_e32 v237, v238, v228
	v_min_f32_e32 v236, v236, v237
.Lrs_nsa_0_0:
	s_mov_b64 s[38:39], 0
.LBB0_833:
	s_andn2_b64 vcc, exec, s[38:39]
	s_cbranch_vccnz .LBB0_835
	v_mov_b32_e32 v237, 0x7f800000
	v_lshrrev_b32_e32 v186, s68, v179
	v_bfe_i32 v186, v186, 0, 1
	v_and_b32_e32 v186, 2.0, v186
	v_subrev_u32_e32 v187, s44, v178
	v_cndmask_b32_e64 v186, v230, v186, s[40:41]
	v_add_u32_e32 v188, v187, v193
	v_cmp_lt_u32_e32 vcc, v188, v186
	v_add_u32_e32 v188, v187, v194
	v_add_u32_e32 v189, v187, v195
	v_cndmask_b32_e32 v148, v228, v148, vcc
	v_cmp_lt_u32_e32 vcc, v188, v186
	s_nop 1
	v_cndmask_b32_e32 v149, v228, v149, vcc
	v_cmp_lt_u32_e32 vcc, v189, v186
	v_add_u32_e32 v189, v187, v196
	v_max3_f32 v188, v148, s88, v149
	v_cndmask_b32_e32 v150, v228, v150, vcc
	v_cmp_lt_u32_e32 vcc, v189, v186
	v_add_u32_e32 v189, v187, v197
	s_nop 0
	v_cndmask_b32_e32 v151, v228, v151, vcc
	v_cmp_lt_u32_e32 vcc, v189, v186
	v_add_u32_e32 v189, v187, v198
	v_max3_f32 v188, v188, v150, v151
	v_cndmask_b32_e32 v152, v228, v152, vcc
	v_cmp_lt_u32_e32 vcc, v189, v186
	v_add_u32_e32 v189, v187, v199
	s_nop 0
	v_cndmask_b32_e32 v153, v228, v153, vcc
	v_cmp_lt_u32_e32 vcc, v189, v186
	v_add_u32_e32 v189, v187, v200
	v_max3_f32 v188, v188, v152, v153
	v_cndmask_b32_e32 v154, v228, v154, vcc
	v_cmp_lt_u32_e32 vcc, v189, v186
	v_add_u32_e32 v189, v187, v201
	s_nop 0
	v_cndmask_b32_e32 v155, v228, v155, vcc
	v_cmp_lt_u32_e32 vcc, v189, v186
	v_add_u32_e32 v189, v187, v202
	v_max3_f32 v188, v188, v154, v155
	v_cndmask_b32_e32 v156, v228, v156, vcc
	v_cmp_lt_u32_e32 vcc, v189, v186
	v_add_u32_e32 v189, v187, v203
	s_nop 0
	v_cndmask_b32_e32 v157, v228, v157, vcc
	v_cmp_lt_u32_e32 vcc, v189, v186
	v_add_u32_e32 v189, v187, v204
	v_max3_f32 v188, v188, v156, v157
	v_cndmask_b32_e32 v158, v228, v158, vcc
	v_cmp_lt_u32_e32 vcc, v189, v186
	v_add_u32_e32 v189, v187, v205
	s_nop 0
	v_cndmask_b32_e32 v159, v228, v159, vcc
	v_cmp_lt_u32_e32 vcc, v189, v186
	v_add_u32_e32 v189, v187, v206
	v_max3_f32 v188, v188, v158, v159
	v_cndmask_b32_e32 v160, v228, v160, vcc
	v_cmp_lt_u32_e32 vcc, v189, v186
	v_add_u32_e32 v189, v187, v207
	v_add_u32_e32 v187, v187, v208
	v_cndmask_b32_e32 v161, v228, v161, vcc
	v_cmp_lt_u32_e32 vcc, v189, v186
	v_max3_f32 v188, v188, v160, v161
	s_nop 0
	v_cndmask_b32_e32 v162, v228, v162, vcc
	v_cmp_lt_u32_e32 vcc, v187, v186
	s_nop 1
	v_cndmask_b32_e32 v163, v228, v163, vcc
	v_max3_f32 v236, v188, v162, v163
.LBB0_835:
	v_mov_b32_e32 v186, v236
	s_nop 1
	v_permlane32_swap_b32_e32 v236, v186
	v_max_f32_e32 v186, v186, v186
	v_max_f32_e32 v187, v236, v236
	v_max_f32_e32 v186, v187, v186
	v_mov_b32_e32 v187, v186
	s_nop 1
	v_permlane16_swap_b32_e32 v186, v187
	v_max3_f32 v236, v2, v186, v187
	v_mul_f32_e32 v186, 0xbe0293ee, v236
	v_min_f32_e32 v186, v186, v237
	v_fmamk_f32 v148, v148, 0x3e0293ee, v186
	v_exp_f32_e32 v148, v148
	v_fmamk_f32 v149, v149, 0x3e0293ee, v186
	v_exp_f32_e32 v149, v149
	v_fmamk_f32 v150, v150, 0x3e0293ee, v186
	v_exp_f32_e32 v150, v150
	v_fmamk_f32 v151, v151, 0x3e0293ee, v186
	v_exp_f32_e32 v151, v151
	v_fmamk_f32 v152, v152, 0x3e0293ee, v186
	v_add_f32_e32 v187, 0, v148
	v_exp_f32_e32 v237, v152
	v_fmamk_f32 v152, v153, 0x3e0293ee, v186
	v_add_f32_e32 v187, v149, v187
	v_exp_f32_e32 v238, v152
	v_fmamk_f32 v152, v154, 0x3e0293ee, v186
	v_add_f32_e32 v187, v150, v187
	v_exp_f32_e32 v239, v152
	v_fmamk_f32 v152, v155, 0x3e0293ee, v186
	v_add_f32_e32 v187, v151, v187
	v_exp_f32_e32 v155, v152
	v_fmamk_f32 v153, v156, 0x3e0293ee, v186
	v_add_f32_e32 v152, v237, v187
	v_exp_f32_e32 v240, v153
	v_fmamk_f32 v153, v157, 0x3e0293ee, v186
	v_add_f32_e32 v152, v238, v152
	v_exp_f32_e32 v241, v153
	v_fmamk_f32 v153, v158, 0x3e0293ee, v186
	v_add_f32_e32 v152, v239, v152
	v_exp_f32_e32 v158, v153
	v_fmamk_f32 v153, v159, 0x3e0293ee, v186
	v_add_f32_e32 v152, v155, v152
	v_exp_f32_e32 v159, v153
	v_fmamk_f32 v153, v160, 0x3e0293ee, v186
	v_add_f32_e32 v152, v240, v152
	v_exp_f32_e32 v160, v153
	v_fmamk_f32 v153, v161, 0x3e0293ee, v186
	v_add_f32_e32 v152, v241, v152
	v_exp_f32_e32 v161, v153
	v_fmamk_f32 v153, v162, 0x3e0293ee, v186
	v_add_f32_e32 v152, v158, v152
	v_exp_f32_e32 v162, v153
	v_fmac_f32_e32 v186, 0x3e0293ee, v163
	v_add_f32_e32 v152, v159, v152
	v_exp_f32_e32 v163, v186
	v_add_f32_e32 v152, v160, v152
	v_add_f32_e32 v152, v161, v152
	v_sub_f32_e32 v2, v2, v236
	v_add_f32_e32 v152, v162, v152
	v_mul_f32_e32 v2, 0x3e0293ee, v2
	v_add_f32_e32 v152, v163, v152
	v_exp_f32_e32 v2, v2
	v_mov_b32_e32 v153, v152
	s_nop 1
	v_permlane32_swap_b32_e32 v152, v153
	v_add_f32_e32 v156, v152, v153
	v_mov_b32_e32 v157, v156
	s_nop 1
	v_permlane16_swap_b32_e32 v156, v157
	v_cmp_neq_f32_e32 vcc, 1.0, v2
	s_cbranch_vccz .LBB0_837
	v_pk_mul_f32 v[114:115], v[114:115], v[2:3] op_sel_hi:[1,0]
	v_pk_mul_f32 v[112:113], v[112:113], v[2:3] op_sel_hi:[1,0]
	v_pk_mul_f32 v[110:111], v[110:111], v[2:3] op_sel_hi:[1,0]
	v_pk_mul_f32 v[108:109], v[108:109], v[2:3] op_sel_hi:[1,0]
	v_pk_mul_f32 v[106:107], v[106:107], v[2:3] op_sel_hi:[1,0]
	v_pk_mul_f32 v[104:105], v[104:105], v[2:3] op_sel_hi:[1,0]
	v_pk_mul_f32 v[102:103], v[102:103], v[2:3] op_sel_hi:[1,0]
	v_pk_mul_f32 v[100:101], v[100:101], v[2:3] op_sel_hi:[1,0]
	v_pk_mul_f32 v[82:83], v[82:83], v[2:3] op_sel_hi:[1,0]
	v_pk_mul_f32 v[80:81], v[80:81], v[2:3] op_sel_hi:[1,0]
	v_pk_mul_f32 v[78:79], v[78:79], v[2:3] op_sel_hi:[1,0]
	v_pk_mul_f32 v[76:77], v[76:77], v[2:3] op_sel_hi:[1,0]
	v_pk_mul_f32 v[74:75], v[74:75], v[2:3] op_sel_hi:[1,0]
	v_pk_mul_f32 v[72:73], v[72:73], v[2:3] op_sel_hi:[1,0]
	v_pk_mul_f32 v[70:71], v[70:71], v[2:3] op_sel_hi:[1,0]
	v_pk_mul_f32 v[68:69], v[68:69], v[2:3] op_sel_hi:[1,0]
.LBB0_837:
	s_xor_b64 s[4:5], s[4:5], -1
	s_andn2_b64 vcc, exec, s[4:5]
	s_mov_b64 s[4:5], -1
	v_cvt_pk_bf16_f32 v152, v148, v149
	v_cvt_pk_bf16_f32 v153, v150, v151
	v_cvt_pk_bf16_f32 v154, v237, v238
	v_cvt_pk_bf16_f32 v155, v239, v155
	v_cvt_pk_bf16_f32 v148, v240, v241
	v_cvt_pk_bf16_f32 v149, v158, v159
	v_cvt_pk_bf16_f32 v150, v160, v161
	v_cvt_pk_bf16_f32 v151, v162, v163
	s_cbranch_vccnz .LBB0_839
	v_max_f32_e32 v158, v135, v135
	v_max_f32_e32 v159, v134, v134
	v_max_f32_e32 v158, v159, v158
	v_max_f32_e32 v159, v139, v139
	v_max_f32_e32 v160, v138, v138
	v_max_f32_e32 v159, v160, v159
	v_max3_f32 v158, v132, v133, v158
	v_max3_f32 v159, v136, v137, v159
	v_max3_f32 v158, v158, s88, v159
	v_max_f32_e32 v159, v143, v143
	v_max_f32_e32 v160, v142, v142
	v_max_f32_e32 v159, v160, v159
	v_max_f32_e32 v160, v147, v147
	v_max_f32_e32 v161, v146, v146
	v_max_f32_e32 v160, v161, v160
	v_max3_f32 v159, v140, v141, v159
	v_max3_f32 v160, v144, v145, v160
	v_max3_f32 v158, v158, v159, v160
	v_mov_b32_e32 v237, 0x7f800000
	s_andn2_b64 vcc, exec, s[40:41]
	s_cbranch_vccnz .Lrs_nsa_0_1
	v_lshrrev_b32_e32 v238, s68, v181
	v_lshlrev_b32_e32 v238, 31, v238
	v_xor_b32_e32 v237, v238, v228
	v_min_f32_e32 v158, v158, v237

.LBB0_839:
	s_andn2_b64 vcc, exec, s[4:5]
	s_cbranch_vccnz .LBB0_841
	v_mov_b32_e32 v237, 0x7f800000
	v_lshrrev_b32_e32 v158, s68, v181
	v_and_b32_e32 v158, 1, v158
	v_mov_b32_e32 v159, s27
	v_cmp_eq_u32_e32 vcc, 1, v158
	s_nop 1
	v_cndmask_b32_e32 v158, 0, v159, vcc
	v_subrev_u32_e32 v159, s44, v180
	v_cndmask_b32_e64 v158, v230, v158, s[40:41]
	v_add_u32_e32 v160, v159, v193
	v_cmp_lt_u32_e32 vcc, v160, v158
	v_add_u32_e32 v160, v159, v194
	v_add_u32_e32 v161, v159, v195
	v_cndmask_b32_e32 v132, v228, v132, vcc
	v_cmp_lt_u32_e32 vcc, v160, v158
	s_nop 1
	v_cndmask_b32_e32 v133, v228, v133, vcc
	v_cmp_lt_u32_e32 vcc, v161, v158
	v_add_u32_e32 v161, v159, v196
	v_max3_f32 v160, v132, s88, v133
	v_cndmask_b32_e32 v134, v228, v134, vcc
	v_cmp_lt_u32_e32 vcc, v161, v158
	v_add_u32_e32 v161, v159, v197
	s_nop 0
	v_cndmask_b32_e32 v135, v228, v135, vcc
	v_cmp_lt_u32_e32 vcc, v161, v158
	v_add_u32_e32 v161, v159, v198
	v_max3_f32 v160, v160, v134, v135
	v_cndmask_b32_e32 v136, v228, v136, vcc
	v_cmp_lt_u32_e32 vcc, v161, v158
	v_add_u32_e32 v161, v159, v199
	s_nop 0
	v_cndmask_b32_e32 v137, v228, v137, vcc
	v_cmp_lt_u32_e32 vcc, v161, v158
	v_add_u32_e32 v161, v159, v200
	v_max3_f32 v160, v160, v136, v137
	v_cndmask_b32_e32 v138, v228, v138, vcc
	v_cmp_lt_u32_e32 vcc, v161, v158
	v_add_u32_e32 v161, v159, v201
	s_nop 0
	v_cndmask_b32_e32 v139, v228, v139, vcc
	v_cmp_lt_u32_e32 vcc, v161, v158
	v_add_u32_e32 v161, v159, v202
	v_max3_f32 v160, v160, v138, v139
	v_cndmask_b32_e32 v140, v228, v140, vcc
	v_cmp_lt_u32_e32 vcc, v161, v158
	v_add_u32_e32 v161, v159, v203
	s_nop 0
	v_cndmask_b32_e32 v141, v228, v141, vcc
	v_cmp_lt_u32_e32 vcc, v161, v158
	v_add_u32_e32 v161, v159, v204
	v_max3_f32 v160, v160, v140, v141
	v_cndmask_b32_e32 v142, v228, v142, vcc
	v_cmp_lt_u32_e32 vcc, v161, v158
	v_add_u32_e32 v161, v159, v205
	s_nop 0
	v_cndmask_b32_e32 v143, v228, v143, vcc
	v_cmp_lt_u32_e32 vcc, v161, v158
	v_add_u32_e32 v161, v159, v206
	v_max3_f32 v160, v160, v142, v143
	v_cndmask_b32_e32 v144, v228, v144, vcc
	v_cmp_lt_u32_e32 vcc, v161, v158
	v_add_u32_e32 v161, v159, v207
	v_add_u32_e32 v159, v159, v208
	v_cndmask_b32_e32 v145, v228, v145, vcc
	v_cmp_lt_u32_e32 vcc, v161, v158
	v_max3_f32 v160, v160, v144, v145
	s_nop 0
	v_cndmask_b32_e32 v146, v228, v146, vcc
	v_cmp_lt_u32_e32 vcc, v159, v158
	s_nop 1
	v_cndmask_b32_e32 v147, v228, v147, vcc
	v_max3_f32 v158, v160, v146, v147
.LBB0_841:
	v_mov_b32_e32 v159, v158
	s_nop 1
	v_permlane32_swap_b32_e32 v158, v159
	v_max_f32_e32 v159, v159, v159
	v_max_f32_e32 v158, v158, v158
	v_max_f32_e32 v158, v158, v159
	v_mov_b32_e32 v159, v158
	s_nop 1
	v_permlane16_swap_b32_e32 v158, v159
	v_max3_f32 v158, v235, v158, v159
	v_mul_f32_e32 v161, 0xbe0293ee, v158
	v_min_f32_e32 v161, v161, v237
	v_sub_f32_e32 v159, v235, v158
	v_fmamk_f32 v132, v132, 0x3e0293ee, v161
	v_mul_f32_e32 v160, 0x3e0293ee, v159
	v_exp_f32_e32 v159, v132
	v_fmamk_f32 v132, v133, 0x3e0293ee, v161
	v_exp_f32_e32 v133, v132
	v_fmamk_f32 v132, v134, 0x3e0293ee, v161
	v_exp_f32_e32 v134, v132
	v_fmamk_f32 v132, v135, 0x3e0293ee, v161
	v_exp_f32_e32 v135, v132
	v_fmamk_f32 v136, v136, 0x3e0293ee, v161
	v_add_f32_e32 v132, 0, v159
	v_exp_f32_e32 v136, v136
	v_fmamk_f32 v137, v137, 0x3e0293ee, v161
	v_add_f32_e32 v132, v133, v132
	v_exp_f32_e32 v137, v137
	v_fmamk_f32 v138, v138, 0x3e0293ee, v161
	v_add_f32_e32 v132, v134, v132
	v_exp_f32_e32 v138, v138
	v_fmamk_f32 v139, v139, 0x3e0293ee, v161
	v_add_f32_e32 v132, v135, v132
	v_exp_f32_e32 v139, v139
	v_fmamk_f32 v140, v140, 0x3e0293ee, v161
	v_add_f32_e32 v132, v136, v132
	v_exp_f32_e32 v140, v140
	v_fmamk_f32 v141, v141, 0x3e0293ee, v161
	v_add_f32_e32 v132, v137, v132
	v_exp_f32_e32 v141, v141
	v_fmamk_f32 v142, v142, 0x3e0293ee, v161
	v_add_f32_e32 v132, v138, v132
	v_exp_f32_e32 v142, v142
	v_fmamk_f32 v143, v143, 0x3e0293ee, v161
	v_add_f32_e32 v132, v139, v132
	v_exp_f32_e32 v143, v143
	v_fmamk_f32 v144, v144, 0x3e0293ee, v161
	v_add_f32_e32 v132, v140, v132
	v_exp_f32_e32 v144, v144
	v_fmamk_f32 v145, v145, 0x3e0293ee, v161
	v_add_f32_e32 v132, v141, v132
	v_exp_f32_e32 v145, v145
	v_fmamk_f32 v146, v146, 0x3e0293ee, v161
	v_add_f32_e32 v132, v142, v132
	v_exp_f32_e32 v146, v146
	v_fmac_f32_e32 v161, 0x3e0293ee, v147
	v_add_f32_e32 v132, v143, v132
	v_exp_f32_e32 v147, v161
	v_add_f32_e32 v132, v144, v132
	v_add_f32_e32 v132, v145, v132
	v_add_f32_e32 v132, v146, v132
	v_add_f32_e32 v161, v147, v132
	v_exp_f32_e32 v132, v160
	v_mov_b32_e32 v160, v161
	s_nop 1
	v_permlane32_swap_b32_e32 v161, v160
	v_add_f32_e32 v160, v161, v160
	v_mov_b32_e32 v161, v160
	s_nop 1
	v_permlane16_swap_b32_e32 v160, v161
	v_cmp_neq_f32_e32 vcc, 1.0, v132
	s_cbranch_vccz .LBB0_843
	v_pk_mul_f32 v[66:67], v[66:67], v[132:133] op_sel_hi:[1,0]
	v_pk_mul_f32 v[64:65], v[64:65], v[132:133] op_sel_hi:[1,0]
	v_pk_mul_f32 v[62:63], v[62:63], v[132:133] op_sel_hi:[1,0]
	v_pk_mul_f32 v[60:61], v[60:61], v[132:133] op_sel_hi:[1,0]
	v_pk_mul_f32 v[58:59], v[58:59], v[132:133] op_sel_hi:[1,0]
	v_pk_mul_f32 v[56:57], v[56:57], v[132:133] op_sel_hi:[1,0]
	v_pk_mul_f32 v[54:55], v[54:55], v[132:133] op_sel_hi:[1,0]
	v_pk_mul_f32 v[52:53], v[52:53], v[132:133] op_sel_hi:[1,0]
	v_pk_mul_f32 v[50:51], v[50:51], v[132:133] op_sel_hi:[1,0]
	v_pk_mul_f32 v[48:49], v[48:49], v[132:133] op_sel_hi:[1,0]
	v_pk_mul_f32 v[46:47], v[46:47], v[132:133] op_sel_hi:[1,0]
	v_pk_mul_f32 v[44:45], v[44:45], v[132:133] op_sel_hi:[1,0]
	v_pk_mul_f32 v[42:43], v[42:43], v[132:133] op_sel_hi:[1,0]
	v_pk_mul_f32 v[40:41], v[40:41], v[132:133] op_sel_hi:[1,0]
	v_pk_mul_f32 v[6:7], v[6:7], v[132:133] op_sel_hi:[1,0]
	v_pk_mul_f32 v[4:5], v[4:5], v[132:133] op_sel_hi:[1,0]

.LBB0_868:
	s_or_b32 s12, s42, 63
	s_sub_i32 s43, s26, s12
	s_cmp_lt_i32 s43, s27
	s_cselect_b64 s[50:51], -1, 0
	s_and_b64 s[4:5], s[50:51], s[4:5]
	s_andn2_b64 vcc, exec, s[4:5]
	s_cbranch_vccnz .LBB0_882
	v_add_u32_e32 v236, v209, v0
	ds_read_b128 v[132:135], v236 offset:36864
	ds_read_b128 v[186:189], v236 offset:36928
	ds_read_b128 v[140:143], v236 offset:41472
	ds_read_b128 v[148:151], v236 offset:46080
	ds_read_b128 v[156:159], v236 offset:50688
	s_cmp_lt_i32 s26, s12
	s_cselect_b64 s[50:51], -1, 0
	s_sub_i32 s4, s57, s42
	s_cmp_ge_i32 s4, s27
	s_waitcnt lgkmcnt(4)
	v_mfma_f32_16x16x32_bf16 v[136:139], v[132:135], v[8:11], 0
	s_cselect_b64 s[4:5], -1, 0
	s_mov_b64 s[38:39], s[50:51]
	s_or_b64 s[4:5], s[38:39], s[4:5]
	v_mfma_f32_16x16x32_bf16 v[132:135], v[132:135], v[24:27], 0
	s_mov_b64 s[38:39], -1
	s_and_b64 vcc, exec, s[4:5]
	s_waitcnt lgkmcnt(3)
	v_mfma_f32_16x16x32_bf16 v[136:139], v[186:189], v[12:15], v[136:139]
	v_mfma_f32_16x16x32_bf16 v[132:135], v[186:189], v[28:31], v[132:135]
	ds_read_b128 v[186:189], v236 offset:41536
	s_waitcnt lgkmcnt(3)
	v_mfma_f32_16x16x32_bf16 v[144:147], v[140:143], v[8:11], 0
	v_mfma_f32_16x16x32_bf16 v[140:143], v[140:143], v[24:27], 0
	s_waitcnt lgkmcnt(0)
	v_mfma_f32_16x16x32_bf16 v[144:147], v[186:189], v[12:15], v[144:147]
	v_mfma_f32_16x16x32_bf16 v[140:143], v[186:189], v[28:31], v[140:143]
	ds_read_b128 v[186:189], v236 offset:46144
	v_mfma_f32_16x16x32_bf16 v[152:155], v[148:151], v[8:11], 0
	v_mfma_f32_16x16x32_bf16 v[148:151], v[148:151], v[24:27], 0
	s_waitcnt lgkmcnt(0)
	v_mfma_f32_16x16x32_bf16 v[152:155], v[186:189], v[12:15], v[152:155]
	v_mfma_f32_16x16x32_bf16 v[148:151], v[186:189], v[28:31], v[148:151]
	ds_read_b128 v[186:189], v236 offset:50752
	v_mfma_f32_16x16x32_bf16 v[160:163], v[156:159], v[8:11], 0
	v_mfma_f32_16x16x32_bf16 v[156:159], v[156:159], v[24:27], 0
	s_waitcnt lgkmcnt(0)
	v_mfma_f32_16x16x32_bf16 v[160:163], v[186:189], v[12:15], v[160:163]
	v_mfma_f32_16x16x32_bf16 v[156:159], v[186:189], v[28:31], v[156:159]
	ds_read_b128 v[186:189], v236 offset:36992
	s_waitcnt lgkmcnt(0)
	v_mfma_f32_16x16x32_bf16 v[136:139], v[186:189], v[16:19], v[136:139]
	v_mfma_f32_16x16x32_bf16 v[132:135], v[186:189], v[32:35], v[132:135]
	ds_read_b128 v[186:189], v236 offset:41600
	s_waitcnt lgkmcnt(0)
	v_mfma_f32_16x16x32_bf16 v[144:147], v[186:189], v[16:19], v[144:147]
	v_mfma_f32_16x16x32_bf16 v[140:143], v[186:189], v[32:35], v[140:143]
	ds_read_b128 v[186:189], v236 offset:46208
	s_waitcnt lgkmcnt(0)
	v_mfma_f32_16x16x32_bf16 v[218:221], v[186:189], v[16:19], v[152:155]
	s_nop 2
	ds_read_b128 v[152:155], v236 offset:37056
	v_mfma_f32_16x16x32_bf16 v[186:189], v[186:189], v[32:35], v[148:151]
	s_nop 2
	ds_read_b128 v[148:151], v236 offset:50816
	s_waitcnt lgkmcnt(0)
	v_mfma_f32_16x16x32_bf16 v[160:163], v[148:151], v[16:19], v[160:163]
	v_mfma_f32_16x16x32_bf16 v[222:225], v[148:151], v[32:35], v[156:159]
	v_mfma_f32_16x16x32_bf16 v[148:151], v[152:155], v[20:23], v[136:139]
	s_nop 2
	ds_read_b128 v[136:139], v236 offset:41664
	v_mfma_f32_16x16x32_bf16 v[132:135], v[152:155], v[36:39], v[132:135]
	s_waitcnt lgkmcnt(0)
	v_mfma_f32_16x16x32_bf16 v[152:155], v[136:139], v[20:23], v[144:147]
	s_nop 2
	ds_read_b128 v[144:147], v236 offset:50880
	v_mfma_f32_16x16x32_bf16 v[136:139], v[136:139], v[36:39], v[140:143]
	s_nop 2
	ds_read_b128 v[140:143], v236 offset:46272
	s_waitcnt lgkmcnt(0)
	v_mfma_f32_16x16x32_bf16 v[156:159], v[140:143], v[20:23], v[218:221]
	v_mfma_f32_16x16x32_bf16 v[140:143], v[140:143], v[36:39], v[186:189]
	v_mfma_f32_16x16x32_bf16 v[160:163], v[144:147], v[20:23], v[160:163]
	v_mfma_f32_16x16x32_bf16 v[144:147], v[144:147], v[36:39], v[222:225]
	s_cbranch_vccnz .LBB0_871
	v_max_f32_e32 v186, v151, v151
	v_max_f32_e32 v187, v150, v150
	v_max_f32_e32 v186, v187, v186
	v_max_f32_e32 v187, v155, v155
	v_max_f32_e32 v188, v154, v154
	v_max_f32_e32 v187, v188, v187
	v_max3_f32 v186, v148, v149, v186
	v_max3_f32 v187, v152, v153, v187
	v_max3_f32 v186, v186, s88, v187
	v_max_f32_e32 v187, v159, v159
	v_max_f32_e32 v188, v158, v158
	v_max_f32_e32 v187, v188, v187
	v_max_f32_e32 v188, v163, v163
	v_max_f32_e32 v189, v162, v162
	v_max_f32_e32 v188, v189, v188
	v_max3_f32 v187, v156, v157, v187
	v_max3_f32 v188, v160, v161, v188
	v_max3_f32 v236, v186, v187, v188
	v_mov_b32_e32 v237, 0x7f800000
	s_andn2_b64 vcc, exec, s[40:41]
	s_cbranch_vccnz .Lrs_nsa_1_0
	v_lshrrev_b32_e32 v238, s56, v179
	v_lshlrev_b32_e32 v238, 31, v238
	v_xor_b32_e32 v237, v238, v228
	v_min_f32_e32 v236, v236, v237

.LBB0_871:
	s_andn2_b64 vcc, exec, s[38:39]
	s_cbranch_vccnz .LBB0_873
	v_mov_b32_e32 v237, 0x7f800000
	v_lshrrev_b32_e32 v186, s56, v179
	v_bfe_i32 v186, v186, 0, 1
	v_and_b32_e32 v186, 2.0, v186
	v_subrev_u32_e32 v187, s42, v178
	v_cndmask_b32_e64 v186, v230, v186, s[40:41]
	v_add_u32_e32 v188, v187, v193
	v_cmp_lt_u32_e32 vcc, v188, v186
	v_add_u32_e32 v188, v187, v194
	v_add_u32_e32 v189, v187, v195
	v_cndmask_b32_e32 v148, v228, v148, vcc
	v_cmp_lt_u32_e32 vcc, v188, v186
	s_nop 1
	v_cndmask_b32_e32 v149, v228, v149, vcc
	v_cmp_lt_u32_e32 vcc, v189, v186
	v_add_u32_e32 v189, v187, v196
	v_max3_f32 v188, v148, s88, v149
	v_cndmask_b32_e32 v150, v228, v150, vcc
	v_cmp_lt_u32_e32 vcc, v189, v186
	v_add_u32_e32 v189, v187, v197
	s_nop 0
	v_cndmask_b32_e32 v151, v228, v151, vcc
	v_cmp_lt_u32_e32 vcc, v189, v186
	v_add_u32_e32 v189, v187, v198
	v_max3_f32 v188, v188, v150, v151
	v_cndmask_b32_e32 v152, v228, v152, vcc
	v_cmp_lt_u32_e32 vcc, v189, v186
	v_add_u32_e32 v189, v187, v199
	s_nop 0
	v_cndmask_b32_e32 v153, v228, v153, vcc
	v_cmp_lt_u32_e32 vcc, v189, v186
	v_add_u32_e32 v189, v187, v200
	v_max3_f32 v188, v188, v152, v153
	v_cndmask_b32_e32 v154, v228, v154, vcc
	v_cmp_lt_u32_e32 vcc, v189, v186
	v_add_u32_e32 v189, v187, v201
	s_nop 0
	v_cndmask_b32_e32 v155, v228, v155, vcc
	v_cmp_lt_u32_e32 vcc, v189, v186
	v_add_u32_e32 v189, v187, v202
	v_max3_f32 v188, v188, v154, v155
	v_cndmask_b32_e32 v156, v228, v156, vcc
	v_cmp_lt_u32_e32 vcc, v189, v186
	v_add_u32_e32 v189, v187, v203
	s_nop 0
	v_cndmask_b32_e32 v157, v228, v157, vcc
	v_cmp_lt_u32_e32 vcc, v189, v186
	v_add_u32_e32 v189, v187, v204
	v_max3_f32 v188, v188, v156, v157
	v_cndmask_b32_e32 v158, v228, v158, vcc
	v_cmp_lt_u32_e32 vcc, v189, v186
	v_add_u32_e32 v189, v187, v205
	s_nop 0
	v_cndmask_b32_e32 v159, v228, v159, vcc
	v_cmp_lt_u32_e32 vcc, v189, v186
	v_add_u32_e32 v189, v187, v206
	v_max3_f32 v188, v188, v158, v159
	v_cndmask_b32_e32 v160, v228, v160, vcc
	v_cmp_lt_u32_e32 vcc, v189, v186
	v_add_u32_e32 v189, v187, v207
	v_add_u32_e32 v187, v187, v208
	v_cndmask_b32_e32 v161, v228, v161, vcc
	v_cmp_lt_u32_e32 vcc, v189, v186
	v_max3_f32 v188, v188, v160, v161
	s_nop 0
	v_cndmask_b32_e32 v162, v228, v162, vcc
	v_cmp_lt_u32_e32 vcc, v187, v186
	s_nop 1
	v_cndmask_b32_e32 v163, v228, v163, vcc
	v_max3_f32 v236, v188, v162, v163

.LBB0_875:
	s_xor_b64 s[4:5], s[4:5], -1
	s_andn2_b64 vcc, exec, s[4:5]
	s_mov_b64 s[4:5], -1
	v_cvt_pk_bf16_f32 v152, v148, v149
	v_cvt_pk_bf16_f32 v153, v150, v151
	v_cvt_pk_bf16_f32 v154, v237, v238
	v_cvt_pk_bf16_f32 v155, v239, v155
	v_cvt_pk_bf16_f32 v148, v240, v241
	v_cvt_pk_bf16_f32 v149, v158, v159
	v_cvt_pk_bf16_f32 v150, v160, v161
	v_cvt_pk_bf16_f32 v151, v162, v163
	s_cbranch_vccnz .LBB0_877
	v_max_f32_e32 v158, v135, v135
	v_max_f32_e32 v159, v134, v134
	v_max_f32_e32 v158, v159, v158
	v_max_f32_e32 v159, v139, v139
	v_max_f32_e32 v160, v138, v138
	v_max_f32_e32 v159, v160, v159
	v_max3_f32 v158, v132, v133, v158
	v_max3_f32 v159, v136, v137, v159
	v_max3_f32 v158, v158, s88, v159
	v_max_f32_e32 v159, v143, v143
	v_max_f32_e32 v160, v142, v142
	v_max_f32_e32 v159, v160, v159
	v_max_f32_e32 v160, v147, v147
	v_max_f32_e32 v161, v146, v146
	v_max_f32_e32 v160, v161, v160
	v_max3_f32 v159, v140, v141, v159
	v_max3_f32 v160, v144, v145, v160
	v_max3_f32 v158, v158, v159, v160
	v_mov_b32_e32 v237, 0x7f800000
	s_andn2_b64 vcc, exec, s[40:41]
	s_cbranch_vccnz .Lrs_nsa_1_1
	v_lshrrev_b32_e32 v238, s56, v181
	v_lshlrev_b32_e32 v238, 31, v238
	v_xor_b32_e32 v237, v238, v228
	v_min_f32_e32 v158, v158, v237

.LBB0_877:
	s_andn2_b64 vcc, exec, s[4:5]
	s_cbranch_vccnz .LBB0_879
	v_mov_b32_e32 v237, 0x7f800000
	v_lshrrev_b32_e32 v158, s56, v181
	v_and_b32_e32 v158, 1, v158
	v_mov_b32_e32 v159, s27
	v_cmp_eq_u32_e32 vcc, 1, v158
	s_nop 1
	v_cndmask_b32_e32 v158, 0, v159, vcc
	v_subrev_u32_e32 v159, s42, v180
	v_cndmask_b32_e64 v158, v230, v158, s[40:41]
	v_add_u32_e32 v160, v159, v193
	v_cmp_lt_u32_e32 vcc, v160, v158
	v_add_u32_e32 v160, v159, v194
	v_add_u32_e32 v161, v159, v195
	v_cndmask_b32_e32 v132, v228, v132, vcc
	v_cmp_lt_u32_e32 vcc, v160, v158
	s_nop 1
	v_cndmask_b32_e32 v133, v228, v133, vcc
	v_cmp_lt_u32_e32 vcc, v161, v158
	v_add_u32_e32 v161, v159, v196
	v_max3_f32 v160, v132, s88, v133
	v_cndmask_b32_e32 v134, v228, v134, vcc
	v_cmp_lt_u32_e32 vcc, v161, v158
	v_add_u32_e32 v161, v159, v197
	s_nop 0
	v_cndmask_b32_e32 v135, v228, v135, vcc
	v_cmp_lt_u32_e32 vcc, v161, v158
	v_add_u32_e32 v161, v159, v198
	v_max3_f32 v160, v160, v134, v135
	v_cndmask_b32_e32 v136, v228, v136, vcc
	v_cmp_lt_u32_e32 vcc, v161, v158
	v_add_u32_e32 v161, v159, v199
	s_nop 0
	v_cndmask_b32_e32 v137, v228, v137, vcc
	v_cmp_lt_u32_e32 vcc, v161, v158
	v_add_u32_e32 v161, v159, v200
	v_max3_f32 v160, v160, v136, v137
	v_cndmask_b32_e32 v138, v228, v138, vcc
	v_cmp_lt_u32_e32 vcc, v161, v158
	v_add_u32_e32 v161, v159, v201
	s_nop 0
	v_cndmask_b32_e32 v139, v228, v139, vcc
	v_cmp_lt_u32_e32 vcc, v161, v158
	v_add_u32_e32 v161, v159, v202
	v_max3_f32 v160, v160, v138, v139
	v_cndmask_b32_e32 v140, v228, v140, vcc
	v_cmp_lt_u32_e32 vcc, v161, v158
	v_add_u32_e32 v161, v159, v203
	s_nop 0
	v_cndmask_b32_e32 v141, v228, v141, vcc
	v_cmp_lt_u32_e32 vcc, v161, v158
	v_add_u32_e32 v161, v159, v204
	v_max3_f32 v160, v160, v140, v141
	v_cndmask_b32_e32 v142, v228, v142, vcc
	v_cmp_lt_u32_e32 vcc, v161, v158
	v_add_u32_e32 v161, v159, v205
	s_nop 0
	v_cndmask_b32_e32 v143, v228, v143, vcc
	v_cmp_lt_u32_e32 vcc, v161, v158
	v_add_u32_e32 v161, v159, v206
	v_max3_f32 v160, v160, v142, v143
	v_cndmask_b32_e32 v144, v228, v144, vcc
	v_cmp_lt_u32_e32 vcc, v161, v158
	v_add_u32_e32 v161, v159, v207
	v_add_u32_e32 v159, v159, v208
	v_cndmask_b32_e32 v145, v228, v145, vcc
	v_cmp_lt_u32_e32 vcc, v161, v158
	v_max3_f32 v160, v160, v144, v145
	s_nop 0
	v_cndmask_b32_e32 v146, v228, v146, vcc
	v_cmp_lt_u32_e32 vcc, v159, v158
	s_nop 1
	v_cndmask_b32_e32 v147, v228, v147, vcc
	v_max3_f32 v158, v160, v146, v147

.LBB0_991:
	s_ashr_i32 s4, s62, 2
	s_lshl_b32 s4, 1, s4
	v_and_b32_e32 v201, s4, v166
	v_and_b32_e32 v200, s4, v167
	v_cmp_eq_u32_e64 s[40:41], 0, v201
	v_cmp_eq_u32_e64 s[42:43], 0, v200
	v_bitop3_b32 v130, s4, v167, v166 bitop3:0xe0
	s_or_b64 s[4:5], s[40:41], s[42:43]
	s_lshl_b32 s28, s62, 6
	v_cmp_ne_u32_e32 vcc, 0, v130
	v_cndmask_b32_e64 v130, 0, 1, s[4:5]
	s_cmp_lt_i32 s26, s28
	v_cmp_ne_u32_e64 s[40:41], 0, v130
	s_cbranch_scc1 .LBB0_1006
	s_cmp_lg_u64 vcc, 0
	s_cselect_b64 s[38:39], -1, 0
	s_or_b32 s4, s28, 63
	s_sub_i32 s5, s21, s4
	s_cmp_lt_i32 s5, 2.0
	s_cselect_b64 s[42:43], -1, 0
	s_and_b64 s[38:39], s[42:43], s[38:39]
	s_andn2_b64 vcc, exec, s[38:39]
	s_cbranch_vccnz .LBB0_1006
	v_add_u32_e32 v218, v193, v162
	ds_read_b128 v[130:133], v218
	ds_read_b128 v[186:189], v218 offset:64
	ds_read_b128 v[138:141], v218 offset:4608
	ds_read_b128 v[146:149], v218 offset:9216
	ds_read_b128 v[154:157], v218 offset:13824
	s_cmp_lg_u64 s[40:41], 0
	s_cselect_b64 s[38:39], -1, 0
	s_cmp_lt_i32 s21, s4
	s_cselect_b64 s[40:41], -1, 0
	s_waitcnt lgkmcnt(4)
	v_mfma_f32_16x16x32_bf16 v[134:137], v[130:133], v[2:5], 0
	s_sub_i32 s4, s26, s28
	s_cmp_gt_i32 s4, 0x3fffffff
	s_cselect_b64 s[4:5], -1, 0
	v_mfma_f32_16x16x32_bf16 v[130:133], v[130:133], v[18:21], 0
	s_mov_b64 s[38:39], s[40:41]
	s_or_b64 s[4:5], s[38:39], s[4:5]
	s_mov_b64 s[38:39], -1
	s_waitcnt lgkmcnt(3)
	v_mfma_f32_16x16x32_bf16 v[134:137], v[186:189], v[6:9], v[134:137]
	s_and_b64 vcc, exec, s[4:5]
	v_mfma_f32_16x16x32_bf16 v[130:133], v[186:189], v[22:25], v[130:133]
	ds_read_b128 v[186:189], v218 offset:4672
	s_waitcnt lgkmcnt(3)
	v_mfma_f32_16x16x32_bf16 v[142:145], v[138:141], v[2:5], 0
	v_mfma_f32_16x16x32_bf16 v[138:141], v[138:141], v[18:21], 0
	s_waitcnt lgkmcnt(0)
	v_mfma_f32_16x16x32_bf16 v[142:145], v[186:189], v[6:9], v[142:145]
	v_mfma_f32_16x16x32_bf16 v[138:141], v[186:189], v[22:25], v[138:141]
	ds_read_b128 v[186:189], v218 offset:9280
	v_mfma_f32_16x16x32_bf16 v[150:153], v[146:149], v[2:5], 0
	v_mfma_f32_16x16x32_bf16 v[146:149], v[146:149], v[18:21], 0
	s_waitcnt lgkmcnt(0)
	v_mfma_f32_16x16x32_bf16 v[150:153], v[186:189], v[6:9], v[150:153]
	v_mfma_f32_16x16x32_bf16 v[146:149], v[186:189], v[22:25], v[146:149]
	ds_read_b128 v[186:189], v218 offset:13888
	v_mfma_f32_16x16x32_bf16 v[158:161], v[154:157], v[2:5], 0
	v_mfma_f32_16x16x32_bf16 v[154:157], v[154:157], v[18:21], 0
	s_waitcnt lgkmcnt(0)
	v_mfma_f32_16x16x32_bf16 v[158:161], v[186:189], v[6:9], v[158:161]
	v_mfma_f32_16x16x32_bf16 v[154:157], v[186:189], v[22:25], v[154:157]
	ds_read_b128 v[186:189], v218 offset:128
	s_waitcnt lgkmcnt(0)
	v_mfma_f32_16x16x32_bf16 v[134:137], v[186:189], v[10:13], v[134:137]
	v_mfma_f32_16x16x32_bf16 v[130:133], v[186:189], v[26:29], v[130:133]
	ds_read_b128 v[186:189], v218 offset:4736
	s_waitcnt lgkmcnt(0)
	v_mfma_f32_16x16x32_bf16 v[142:145], v[186:189], v[10:13], v[142:145]
	v_mfma_f32_16x16x32_bf16 v[138:141], v[186:189], v[26:29], v[138:141]
	ds_read_b128 v[186:189], v218 offset:9344
	s_waitcnt lgkmcnt(0)
	v_mfma_f32_16x16x32_bf16 v[202:205], v[186:189], v[10:13], v[150:153]
	s_nop 2
	ds_read_b128 v[150:153], v218 offset:192
	v_mfma_f32_16x16x32_bf16 v[186:189], v[186:189], v[26:29], v[146:149]
	s_nop 2
	ds_read_b128 v[146:149], v218 offset:13952
	s_waitcnt lgkmcnt(0)
	v_mfma_f32_16x16x32_bf16 v[158:161], v[146:149], v[10:13], v[158:161]
	v_mfma_f32_16x16x32_bf16 v[206:209], v[146:149], v[26:29], v[154:157]
	v_mfma_f32_16x16x32_bf16 v[146:149], v[150:153], v[14:17], v[134:137]
	s_nop 2
	ds_read_b128 v[134:137], v218 offset:4800
	v_mfma_f32_16x16x32_bf16 v[130:133], v[150:153], v[30:33], v[130:133]
	s_waitcnt lgkmcnt(0)
	v_mfma_f32_16x16x32_bf16 v[150:153], v[134:137], v[14:17], v[142:145]
	s_nop 2
	ds_read_b128 v[142:145], v218 offset:14016
	v_mfma_f32_16x16x32_bf16 v[134:137], v[134:137], v[30:33], v[138:141]
	s_nop 2
	ds_read_b128 v[138:141], v218 offset:9408
	s_waitcnt lgkmcnt(0)
	v_mfma_f32_16x16x32_bf16 v[154:157], v[138:141], v[14:17], v[202:205]
	v_mfma_f32_16x16x32_bf16 v[138:141], v[138:141], v[30:33], v[186:189]
	v_mfma_f32_16x16x32_bf16 v[158:161], v[142:145], v[14:17], v[158:161]
	v_mfma_f32_16x16x32_bf16 v[142:145], v[142:145], v[30:33], v[206:209]
	s_cbranch_vccnz .LBB0_995
	v_max_f32_e32 v186, v149, v149
	v_max_f32_e32 v187, v148, v148
	v_max_f32_e32 v186, v187, v186
	v_max_f32_e32 v187, v153, v153
	v_max_f32_e32 v188, v152, v152
	v_max_f32_e32 v187, v188, v187
	v_max3_f32 v186, v146, v147, v186
	v_max3_f32 v187, v150, v151, v187
	v_max3_f32 v186, v186, s88, v187
	v_max_f32_e32 v187, v157, v157
	v_max_f32_e32 v188, v156, v156
	v_max_f32_e32 v187, v188, v187
	v_max_f32_e32 v188, v161, v161
	v_max_f32_e32 v189, v160, v160
	v_max_f32_e32 v188, v189, v188
	v_max3_f32 v187, v154, v155, v187
	v_max3_f32 v188, v158, v159, v188
	v_max3_f32 v202, v186, v187, v188
	v_cmp_eq_u32_e32 vcc, 0, v201
	v_mov_b32_e32 v203, 0x7f800000
	s_nop 1
	v_cndmask_b32_e32 v203, v203, v228, vcc
	v_min_f32_e32 v202, v202, v203
	s_mov_b64 s[38:39], 0
.LBB0_995:
	s_andn2_b64 vcc, exec, s[38:39]
	s_cbranch_vccnz .LBB0_997
	v_mov_b32_e32 v203, 0x7f800000
	v_cmp_eq_u32_e32 vcc, 0, v201
	v_subrev_u32_e32 v187, s28, v164
	v_add_u32_e32 v188, v187, v173
	v_cndmask_b32_e64 v186, 2.0, 0, vcc
	v_cmp_lt_u32_e32 vcc, v188, v186
	v_add_u32_e32 v188, v187, v174
	v_add_u32_e32 v189, v187, v175
	v_cndmask_b32_e32 v146, v228, v146, vcc
	v_cmp_lt_u32_e32 vcc, v188, v186
	s_nop 1
	v_cndmask_b32_e32 v147, v228, v147, vcc
	v_cmp_lt_u32_e32 vcc, v189, v186
	v_add_u32_e32 v189, v187, v176
	v_max3_f32 v188, v146, s88, v147
	v_cndmask_b32_e32 v148, v228, v148, vcc
	v_cmp_lt_u32_e32 vcc, v189, v186
	v_add_u32_e32 v189, v187, v177
	s_nop 0
	v_cndmask_b32_e32 v149, v228, v149, vcc
	v_cmp_lt_u32_e32 vcc, v189, v186
	v_add_u32_e32 v189, v187, v178
	v_max3_f32 v188, v188, v148, v149
	v_cndmask_b32_e32 v150, v228, v150, vcc
	v_cmp_lt_u32_e32 vcc, v189, v186
	v_add_u32_e32 v189, v187, v179
	s_nop 0
	v_cndmask_b32_e32 v151, v228, v151, vcc
	v_cmp_lt_u32_e32 vcc, v189, v186
	v_add_u32_e32 v189, v187, v180
	v_max3_f32 v188, v188, v150, v151
	v_cndmask_b32_e32 v152, v228, v152, vcc
	v_cmp_lt_u32_e32 vcc, v189, v186
	v_add_u32_e32 v189, v187, v181
	s_nop 0
	v_cndmask_b32_e32 v153, v228, v153, vcc
	v_cmp_lt_u32_e32 vcc, v189, v186
	v_add_u32_e32 v189, v187, v182
	v_max3_f32 v188, v188, v152, v153
	v_cndmask_b32_e32 v154, v228, v154, vcc
	v_cmp_lt_u32_e32 vcc, v189, v186
	v_add_u32_e32 v189, v187, v183
	s_nop 0
	v_cndmask_b32_e32 v155, v228, v155, vcc
	v_cmp_lt_u32_e32 vcc, v189, v186
	v_add_u32_e32 v189, v187, v184
	v_max3_f32 v188, v188, v154, v155
	v_cndmask_b32_e32 v156, v228, v156, vcc
	v_cmp_lt_u32_e32 vcc, v189, v186
	v_add_u32_e32 v189, v187, v185
	s_nop 0
	v_cndmask_b32_e32 v157, v228, v157, vcc
	v_cmp_lt_u32_e32 vcc, v189, v186
	v_add_u32_e32 v189, v187, v190
	v_max3_f32 v188, v188, v156, v157
	v_cndmask_b32_e32 v158, v228, v158, vcc
	v_cmp_lt_u32_e32 vcc, v189, v186
	v_add_u32_e32 v189, v187, v191
	v_add_u32_e32 v187, v187, v192
	v_cndmask_b32_e32 v159, v228, v159, vcc
	v_cmp_lt_u32_e32 vcc, v189, v186
	v_max3_f32 v188, v188, v158, v159
	s_nop 0
	v_cndmask_b32_e32 v160, v228, v160, vcc
	v_cmp_lt_u32_e32 vcc, v187, v186
	s_nop 1
	v_cndmask_b32_e32 v161, v228, v161, vcc
	v_max3_f32 v202, v188, v160, v161
.LBB0_997:
	v_mov_b32_e32 v186, v202
	s_nop 1
	v_permlane32_swap_b32_e32 v202, v186
	v_max_f32_e32 v186, v186, v186
	v_max_f32_e32 v187, v202, v202
	v_max_f32_e32 v186, v187, v186
	v_mov_b32_e32 v187, v186
	s_nop 1
	v_permlane16_swap_b32_e32 v186, v187
	v_max3_f32 v201, v199, v186, v187
	v_mul_f32_e32 v187, 0xbe0293ee, v201
	v_min_f32_e32 v187, v187, v203
	v_fmamk_f32 v146, v146, 0x3e0293ee, v187
	v_exp_f32_e32 v146, v146
	v_fmamk_f32 v147, v147, 0x3e0293ee, v187
	v_exp_f32_e32 v147, v147
	v_fmamk_f32 v148, v148, 0x3e0293ee, v187
	v_exp_f32_e32 v148, v148
	v_fmamk_f32 v149, v149, 0x3e0293ee, v187
	v_exp_f32_e32 v149, v149
	v_fmamk_f32 v150, v150, 0x3e0293ee, v187
	v_sub_f32_e32 v186, v199, v201
	v_add_f32_e32 v188, 0, v146
	v_exp_f32_e32 v199, v150
	v_fmamk_f32 v150, v151, 0x3e0293ee, v187
	v_add_f32_e32 v188, v147, v188
	v_exp_f32_e32 v202, v150
	v_fmamk_f32 v150, v152, 0x3e0293ee, v187
	v_add_f32_e32 v188, v148, v188
	v_exp_f32_e32 v203, v150
	v_fmamk_f32 v150, v153, 0x3e0293ee, v187
	v_add_f32_e32 v188, v149, v188
	v_exp_f32_e32 v153, v150
	v_fmamk_f32 v151, v154, 0x3e0293ee, v187
	v_add_f32_e32 v150, v199, v188
	v_exp_f32_e32 v204, v151
	v_fmamk_f32 v151, v155, 0x3e0293ee, v187
	v_add_f32_e32 v150, v202, v150
	v_exp_f32_e32 v205, v151
	v_fmamk_f32 v151, v156, 0x3e0293ee, v187
	v_add_f32_e32 v150, v203, v150
	v_exp_f32_e32 v206, v151
	v_fmamk_f32 v151, v157, 0x3e0293ee, v187
	v_add_f32_e32 v150, v153, v150
	v_exp_f32_e32 v157, v151
	v_fmamk_f32 v151, v158, 0x3e0293ee, v187
	v_add_f32_e32 v150, v204, v150
	v_exp_f32_e32 v158, v151
	v_fmamk_f32 v151, v159, 0x3e0293ee, v187
	v_add_f32_e32 v150, v205, v150
	v_exp_f32_e32 v159, v151
	v_fmamk_f32 v151, v160, 0x3e0293ee, v187
	v_add_f32_e32 v150, v206, v150
	v_exp_f32_e32 v160, v151
	v_fmac_f32_e32 v187, 0x3e0293ee, v161
	v_add_f32_e32 v150, v157, v150
	v_exp_f32_e32 v161, v187
	v_add_f32_e32 v150, v158, v150
	v_add_f32_e32 v150, v159, v150
	v_add_f32_e32 v150, v160, v150
	v_mul_f32_e32 v186, 0x3e0293ee, v186
	v_add_f32_e32 v150, v161, v150
	v_exp_f32_e32 v154, v186
	v_mov_b32_e32 v151, v150
	s_nop 1
	v_permlane32_swap_b32_e32 v150, v151
	v_add_f32_e32 v155, v150, v151
	v_mov_b32_e32 v156, v155
	s_nop 1
	v_permlane16_swap_b32_e32 v155, v156
	v_cmp_neq_f32_e32 vcc, 1.0, v154
	s_cbranch_vccz .LBB0_999
	v_pk_mul_f32 v[112:113], v[112:113], v[154:155] op_sel_hi:[1,0]
	v_pk_mul_f32 v[110:111], v[110:111], v[154:155] op_sel_hi:[1,0]
	v_pk_mul_f32 v[108:109], v[108:109], v[154:155] op_sel_hi:[1,0]
	v_pk_mul_f32 v[106:107], v[106:107], v[154:155] op_sel_hi:[1,0]
	v_pk_mul_f32 v[104:105], v[104:105], v[154:155] op_sel_hi:[1,0]
	v_pk_mul_f32 v[102:103], v[102:103], v[154:155] op_sel_hi:[1,0]
	v_pk_mul_f32 v[100:101], v[100:101], v[154:155] op_sel_hi:[1,0]
	v_pk_mul_f32 v[98:99], v[98:99], v[154:155] op_sel_hi:[1,0]
	v_pk_mul_f32 v[96:97], v[96:97], v[154:155] op_sel_hi:[1,0]
	v_pk_mul_f32 v[94:95], v[94:95], v[154:155] op_sel_hi:[1,0]
	v_pk_mul_f32 v[92:93], v[92:93], v[154:155] op_sel_hi:[1,0]
	v_pk_mul_f32 v[90:91], v[90:91], v[154:155] op_sel_hi:[1,0]
	v_pk_mul_f32 v[88:89], v[88:89], v[154:155] op_sel_hi:[1,0]
	v_pk_mul_f32 v[86:87], v[86:87], v[154:155] op_sel_hi:[1,0]
	v_pk_mul_f32 v[84:85], v[84:85], v[154:155] op_sel_hi:[1,0]
	v_pk_mul_f32 v[82:83], v[82:83], v[154:155] op_sel_hi:[1,0]
.LBB0_999:
	s_xor_b64 s[4:5], s[4:5], -1
	s_andn2_b64 vcc, exec, s[4:5]
	s_mov_b64 s[4:5], -1
	v_cvt_pk_bf16_f32 v150, v146, v147
	v_cvt_pk_bf16_f32 v151, v148, v149
	v_cvt_pk_bf16_f32 v152, v199, v202
	v_cvt_pk_bf16_f32 v153, v203, v153
	v_cvt_pk_bf16_f32 v146, v204, v205
	v_cvt_pk_bf16_f32 v147, v206, v157
	v_cvt_pk_bf16_f32 v148, v158, v159
	v_cvt_pk_bf16_f32 v149, v160, v161
	s_cbranch_vccnz .LBB0_1001
	v_max_f32_e32 v157, v133, v133
	v_max_f32_e32 v158, v132, v132
	v_max_f32_e32 v157, v158, v157
	v_max_f32_e32 v158, v137, v137
	v_max_f32_e32 v159, v136, v136
	v_max_f32_e32 v158, v159, v158
	v_max3_f32 v157, v130, v131, v157
	v_max3_f32 v158, v134, v135, v158
	v_max3_f32 v157, v157, s88, v158
	v_max_f32_e32 v158, v141, v141
	v_max_f32_e32 v159, v140, v140
	v_max_f32_e32 v158, v159, v158
	v_max_f32_e32 v159, v145, v145
	v_max_f32_e32 v160, v144, v144
	v_max_f32_e32 v159, v160, v159
	v_max3_f32 v158, v138, v139, v158
	v_max3_f32 v159, v142, v143, v159
	v_max3_f32 v157, v157, v158, v159
	v_cmp_eq_u32_e32 vcc, 0, v200
	v_mov_b32_e32 v203, 0x7f800000
	s_nop 1
	v_cndmask_b32_e32 v203, v203, v228, vcc
	v_min_f32_e32 v157, v157, v203
	s_mov_b64 s[4:5], 0
.LBB0_1001:
	s_andn2_b64 vcc, exec, s[4:5]
	s_cbranch_vccnz .LBB0_1003
	v_mov_b32_e32 v203, 0x7f800000
	v_cmp_eq_u32_e32 vcc, 0, v200
	v_subrev_u32_e32 v158, s28, v165
	v_add_u32_e32 v159, v158, v173
	v_cndmask_b32_e64 v157, 2.0, 0, vcc
	v_cmp_lt_u32_e32 vcc, v159, v157
	v_add_u32_e32 v159, v158, v174
	v_add_u32_e32 v160, v158, v175
	v_cndmask_b32_e32 v130, v228, v130, vcc
	v_cmp_lt_u32_e32 vcc, v159, v157
	s_nop 1
	v_cndmask_b32_e32 v131, v228, v131, vcc
	v_cmp_lt_u32_e32 vcc, v160, v157
	v_add_u32_e32 v160, v158, v176
	v_max3_f32 v159, v130, s88, v131
	v_cndmask_b32_e32 v132, v228, v132, vcc
	v_cmp_lt_u32_e32 vcc, v160, v157
	v_add_u32_e32 v160, v158, v177
	s_nop 0
	v_cndmask_b32_e32 v133, v228, v133, vcc
	v_cmp_lt_u32_e32 vcc, v160, v157
	v_add_u32_e32 v160, v158, v178
	v_max3_f32 v159, v159, v132, v133
	v_cndmask_b32_e32 v134, v228, v134, vcc
	v_cmp_lt_u32_e32 vcc, v160, v157
	v_add_u32_e32 v160, v158, v179
	s_nop 0
	v_cndmask_b32_e32 v135, v228, v135, vcc
	v_cmp_lt_u32_e32 vcc, v160, v157
	v_add_u32_e32 v160, v158, v180
	v_max3_f32 v159, v159, v134, v135
	v_cndmask_b32_e32 v136, v228, v136, vcc
	v_cmp_lt_u32_e32 vcc, v160, v157
	v_add_u32_e32 v160, v158, v181
	s_nop 0
	v_cndmask_b32_e32 v137, v228, v137, vcc
	v_cmp_lt_u32_e32 vcc, v160, v157
	v_add_u32_e32 v160, v158, v182
	v_max3_f32 v159, v159, v136, v137
	v_cndmask_b32_e32 v138, v228, v138, vcc
	v_cmp_lt_u32_e32 vcc, v160, v157
	v_add_u32_e32 v160, v158, v183
	s_nop 0
	v_cndmask_b32_e32 v139, v228, v139, vcc
	v_cmp_lt_u32_e32 vcc, v160, v157
	v_add_u32_e32 v160, v158, v184
	v_max3_f32 v159, v159, v138, v139
	v_cndmask_b32_e32 v140, v228, v140, vcc
	v_cmp_lt_u32_e32 vcc, v160, v157
	v_add_u32_e32 v160, v158, v185
	s_nop 0
	v_cndmask_b32_e32 v141, v228, v141, vcc
	v_cmp_lt_u32_e32 vcc, v160, v157
	v_add_u32_e32 v160, v158, v190
	v_max3_f32 v159, v159, v140, v141
	v_cndmask_b32_e32 v142, v228, v142, vcc
	v_cmp_lt_u32_e32 vcc, v160, v157
	v_add_u32_e32 v160, v158, v191
	v_add_u32_e32 v158, v158, v192
	v_cndmask_b32_e32 v143, v228, v143, vcc
	v_cmp_lt_u32_e32 vcc, v160, v157
	v_max3_f32 v159, v159, v142, v143
	s_nop 0
	v_cndmask_b32_e32 v144, v228, v144, vcc
	v_cmp_lt_u32_e32 vcc, v158, v157
	s_nop 1
	v_cndmask_b32_e32 v145, v228, v145, vcc
	v_max3_f32 v157, v159, v144, v145
.LBB0_1003:
	v_mov_b32_e32 v158, v157
	s_nop 1
	v_permlane32_swap_b32_e32 v157, v158
	v_max_f32_e32 v158, v158, v158
	v_max_f32_e32 v157, v157, v157
	v_max_f32_e32 v157, v157, v158
	v_mov_b32_e32 v158, v157
	s_nop 1
	v_permlane16_swap_b32_e32 v157, v158
	v_max3_f32 v157, v198, v157, v158
	v_mul_f32_e32 v160, 0xbe0293ee, v157
	v_min_f32_e32 v160, v160, v203
	v_sub_f32_e32 v158, v198, v157
	v_fmamk_f32 v130, v130, 0x3e0293ee, v160
	v_mul_f32_e32 v159, 0x3e0293ee, v158
	v_exp_f32_e32 v158, v130
	v_fmamk_f32 v130, v131, 0x3e0293ee, v160
	v_exp_f32_e32 v131, v130
	v_fmamk_f32 v130, v132, 0x3e0293ee, v160
	v_exp_f32_e32 v132, v130
	v_fmamk_f32 v130, v133, 0x3e0293ee, v160
	v_exp_f32_e32 v133, v130
	v_fmamk_f32 v134, v134, 0x3e0293ee, v160
	v_add_f32_e32 v130, 0, v158
	v_exp_f32_e32 v134, v134
	v_fmamk_f32 v135, v135, 0x3e0293ee, v160
	v_add_f32_e32 v130, v131, v130
	v_exp_f32_e32 v135, v135
	v_fmamk_f32 v136, v136, 0x3e0293ee, v160
	v_add_f32_e32 v130, v132, v130
	v_exp_f32_e32 v136, v136
	v_fmamk_f32 v137, v137, 0x3e0293ee, v160
	v_add_f32_e32 v130, v133, v130
	v_exp_f32_e32 v137, v137
	v_fmamk_f32 v138, v138, 0x3e0293ee, v160
	v_add_f32_e32 v130, v134, v130
	v_exp_f32_e32 v138, v138
	v_fmamk_f32 v139, v139, 0x3e0293ee, v160
	v_add_f32_e32 v130, v135, v130
	v_exp_f32_e32 v139, v139
	v_fmamk_f32 v140, v140, 0x3e0293ee, v160
	v_add_f32_e32 v130, v136, v130
	v_exp_f32_e32 v140, v140
	v_fmamk_f32 v141, v141, 0x3e0293ee, v160
	v_add_f32_e32 v130, v137, v130
	v_exp_f32_e32 v141, v141
	v_fmamk_f32 v142, v142, 0x3e0293ee, v160
	v_add_f32_e32 v130, v138, v130
	v_exp_f32_e32 v142, v142
	v_fmamk_f32 v143, v143, 0x3e0293ee, v160
	v_add_f32_e32 v130, v139, v130
	v_exp_f32_e32 v143, v143
	v_fmamk_f32 v144, v144, 0x3e0293ee, v160
	v_add_f32_e32 v130, v140, v130
	v_exp_f32_e32 v144, v144
	v_fmac_f32_e32 v160, 0x3e0293ee, v145
	v_add_f32_e32 v130, v141, v130
	v_exp_f32_e32 v145, v160
	v_add_f32_e32 v130, v142, v130
	v_add_f32_e32 v130, v143, v130
	v_add_f32_e32 v130, v144, v130
	v_add_f32_e32 v160, v145, v130
	v_exp_f32_e32 v130, v159
	v_mov_b32_e32 v159, v160
	s_nop 1
	v_permlane32_swap_b32_e32 v160, v159
	v_add_f32_e32 v159, v160, v159
	v_mov_b32_e32 v160, v159
	s_nop 1
	v_permlane16_swap_b32_e32 v159, v160
	v_cmp_neq_f32_e32 vcc, 1.0, v130
	s_cbranch_vccz .LBB0_1005
	v_pk_mul_f32 v[80:81], v[80:81], v[130:131] op_sel_hi:[1,0]
	v_pk_mul_f32 v[78:79], v[78:79], v[130:131] op_sel_hi:[1,0]
	v_pk_mul_f32 v[76:77], v[76:77], v[130:131] op_sel_hi:[1,0]
	v_pk_mul_f32 v[74:75], v[74:75], v[130:131] op_sel_hi:[1,0]
	v_pk_mul_f32 v[72:73], v[72:73], v[130:131] op_sel_hi:[1,0]
	v_pk_mul_f32 v[70:71], v[70:71], v[130:131] op_sel_hi:[1,0]
	v_pk_mul_f32 v[68:69], v[68:69], v[130:131] op_sel_hi:[1,0]
	v_pk_mul_f32 v[66:67], v[66:67], v[130:131] op_sel_hi:[1,0]
	v_pk_mul_f32 v[64:65], v[64:65], v[130:131] op_sel_hi:[1,0]
	v_pk_mul_f32 v[62:63], v[62:63], v[130:131] op_sel_hi:[1,0]
	v_pk_mul_f32 v[60:61], v[60:61], v[130:131] op_sel_hi:[1,0]
	v_pk_mul_f32 v[58:59], v[58:59], v[130:131] op_sel_hi:[1,0]
	v_pk_mul_f32 v[56:57], v[56:57], v[130:131] op_sel_hi:[1,0]
	v_pk_mul_f32 v[54:55], v[54:55], v[130:131] op_sel_hi:[1,0]
	v_pk_mul_f32 v[52:53], v[52:53], v[130:131] op_sel_hi:[1,0]
	v_pk_mul_f32 v[50:51], v[50:51], v[130:131] op_sel_hi:[1,0]

.LBB0_1027:
	s_ashr_i32 s4, s64, 2
	s_lshl_b32 s4, 1, s4
	v_and_b32_e32 v201, s4, v166
	v_and_b32_e32 v200, s4, v167
	v_cmp_eq_u32_e64 s[42:43], 0, v201
	v_cmp_eq_u32_e64 s[44:45], 0, v200
	v_bitop3_b32 v130, s4, v167, v166 bitop3:0xe0
	s_or_b64 s[4:5], s[42:43], s[44:45]
	s_lshl_b32 s28, s64, 6
	v_cmp_ne_u32_e32 vcc, 0, v130
	v_cndmask_b32_e64 v130, 0, 1, s[4:5]
	s_cmp_lt_i32 s26, s28
	v_cmp_ne_u32_e64 s[42:43], 0, v130
	s_cbranch_scc1 .LBB0_1042
	s_cmp_lg_u64 vcc, 0
	s_cselect_b64 s[38:39], -1, 0
	s_or_b32 s4, s28, 63
	s_sub_i32 s5, s21, s4
	s_cmp_lt_i32 s5, 2.0
	s_cselect_b64 s[44:45], -1, 0
	s_and_b64 s[38:39], s[44:45], s[38:39]
	s_andn2_b64 vcc, exec, s[38:39]
	s_cbranch_vccnz .LBB0_1042
	v_add_u32_e32 v218, v193, v162
	ds_read_b128 v[130:133], v218 offset:36864
	ds_read_b128 v[186:189], v218 offset:36928
	ds_read_b128 v[138:141], v218 offset:41472
	ds_read_b128 v[146:149], v218 offset:46080
	ds_read_b128 v[154:157], v218 offset:50688
	s_cmp_lg_u64 s[42:43], 0
	s_cselect_b64 s[38:39], -1, 0
	s_cmp_lt_i32 s21, s4
	s_cselect_b64 s[42:43], -1, 0
	s_waitcnt lgkmcnt(4)
	v_mfma_f32_16x16x32_bf16 v[134:137], v[130:133], v[2:5], 0
	s_sub_i32 s4, s26, s28
	s_cmp_gt_i32 s4, 0x3fffffff
	s_cselect_b64 s[4:5], -1, 0
	v_mfma_f32_16x16x32_bf16 v[130:133], v[130:133], v[18:21], 0
	s_mov_b64 s[38:39], s[42:43]
	s_or_b64 s[4:5], s[38:39], s[4:5]
	s_mov_b64 s[38:39], -1
	s_waitcnt lgkmcnt(3)
	v_mfma_f32_16x16x32_bf16 v[134:137], v[186:189], v[6:9], v[134:137]
	s_and_b64 vcc, exec, s[4:5]
	v_mfma_f32_16x16x32_bf16 v[130:133], v[186:189], v[22:25], v[130:133]
	ds_read_b128 v[186:189], v218 offset:41536
	s_waitcnt lgkmcnt(3)
	v_mfma_f32_16x16x32_bf16 v[142:145], v[138:141], v[2:5], 0
	v_mfma_f32_16x16x32_bf16 v[138:141], v[138:141], v[18:21], 0
	s_waitcnt lgkmcnt(0)
	v_mfma_f32_16x16x32_bf16 v[142:145], v[186:189], v[6:9], v[142:145]
	v_mfma_f32_16x16x32_bf16 v[138:141], v[186:189], v[22:25], v[138:141]
	ds_read_b128 v[186:189], v218 offset:46144
	v_mfma_f32_16x16x32_bf16 v[150:153], v[146:149], v[2:5], 0
	v_mfma_f32_16x16x32_bf16 v[146:149], v[146:149], v[18:21], 0
	s_waitcnt lgkmcnt(0)
	v_mfma_f32_16x16x32_bf16 v[150:153], v[186:189], v[6:9], v[150:153]
	v_mfma_f32_16x16x32_bf16 v[146:149], v[186:189], v[22:25], v[146:149]
	ds_read_b128 v[186:189], v218 offset:50752
	v_mfma_f32_16x16x32_bf16 v[158:161], v[154:157], v[2:5], 0
	v_mfma_f32_16x16x32_bf16 v[154:157], v[154:157], v[18:21], 0
	s_waitcnt lgkmcnt(0)
	v_mfma_f32_16x16x32_bf16 v[158:161], v[186:189], v[6:9], v[158:161]
	v_mfma_f32_16x16x32_bf16 v[154:157], v[186:189], v[22:25], v[154:157]
	ds_read_b128 v[186:189], v218 offset:36992
	s_waitcnt lgkmcnt(0)
	v_mfma_f32_16x16x32_bf16 v[134:137], v[186:189], v[10:13], v[134:137]
	v_mfma_f32_16x16x32_bf16 v[130:133], v[186:189], v[26:29], v[130:133]
	ds_read_b128 v[186:189], v218 offset:41600
	s_waitcnt lgkmcnt(0)
	v_mfma_f32_16x16x32_bf16 v[142:145], v[186:189], v[10:13], v[142:145]
	v_mfma_f32_16x16x32_bf16 v[138:141], v[186:189], v[26:29], v[138:141]
	ds_read_b128 v[186:189], v218 offset:46208
	s_waitcnt lgkmcnt(0)
	v_mfma_f32_16x16x32_bf16 v[202:205], v[186:189], v[10:13], v[150:153]
	s_nop 2
	ds_read_b128 v[150:153], v218 offset:37056
	v_mfma_f32_16x16x32_bf16 v[186:189], v[186:189], v[26:29], v[146:149]
	s_nop 2
	ds_read_b128 v[146:149], v218 offset:50816
	s_waitcnt lgkmcnt(0)
	v_mfma_f32_16x16x32_bf16 v[158:161], v[146:149], v[10:13], v[158:161]
	v_mfma_f32_16x16x32_bf16 v[206:209], v[146:149], v[26:29], v[154:157]
	v_mfma_f32_16x16x32_bf16 v[146:149], v[150:153], v[14:17], v[134:137]
	s_nop 2
	ds_read_b128 v[134:137], v218 offset:41664
	v_mfma_f32_16x16x32_bf16 v[130:133], v[150:153], v[30:33], v[130:133]
	s_waitcnt lgkmcnt(0)
	v_mfma_f32_16x16x32_bf16 v[150:153], v[134:137], v[14:17], v[142:145]
	s_nop 2
	ds_read_b128 v[142:145], v218 offset:50880
	v_mfma_f32_16x16x32_bf16 v[134:137], v[134:137], v[30:33], v[138:141]
	s_nop 2
	ds_read_b128 v[138:141], v218 offset:46272
	s_waitcnt lgkmcnt(0)
	v_mfma_f32_16x16x32_bf16 v[154:157], v[138:141], v[14:17], v[202:205]
	v_mfma_f32_16x16x32_bf16 v[138:141], v[138:141], v[30:33], v[186:189]
	v_mfma_f32_16x16x32_bf16 v[158:161], v[142:145], v[14:17], v[158:161]
	v_mfma_f32_16x16x32_bf16 v[142:145], v[142:145], v[30:33], v[206:209]
	s_cbranch_vccnz .LBB0_1031
	v_max_f32_e32 v186, v149, v149
	v_max_f32_e32 v187, v148, v148
	v_max_f32_e32 v186, v187, v186
	v_max_f32_e32 v187, v153, v153
	v_max_f32_e32 v188, v152, v152
	v_max_f32_e32 v187, v188, v187
	v_max3_f32 v186, v146, v147, v186
	v_max3_f32 v187, v150, v151, v187
	v_max3_f32 v186, v186, s88, v187
	v_max_f32_e32 v187, v157, v157
	v_max_f32_e32 v188, v156, v156
	v_max_f32_e32 v187, v188, v187
	v_max_f32_e32 v188, v161, v161
	v_max_f32_e32 v189, v160, v160
	v_max_f32_e32 v188, v189, v188
	v_max3_f32 v187, v154, v155, v187
	v_max3_f32 v188, v158, v159, v188
	v_max3_f32 v202, v186, v187, v188
	v_cmp_eq_u32_e32 vcc, 0, v201
	v_mov_b32_e32 v203, 0x7f800000
	s_nop 1
	v_cndmask_b32_e32 v203, v203, v228, vcc
	v_min_f32_e32 v202, v202, v203
	s_mov_b64 s[38:39], 0
